# decode stream page-ids from VGPR lanes + counted vmcnt; attention: s_setprio 1 during the MFMA phase
# speedup vs baseline: 1.0280x; 1.0099x over previous
; #define LAS __attribute__((address_space(3)))
; __device__ __forceinline__ void sample_attn_seq(const Args& a, LAS unsigned char* lds, int s, int wv) {
;     ...
;     const int g4 = lane >> 4, l15 = lane & 15;
;     const LAS unsigned char* qfp = lds + SA_QIMG + l15 * SA_PITCH + 8 * g4 * 2;
;     LAS unsigned char* kt = lds + SA_KT + wave * 9472;
;     const unsigned ktb = (unsigned)(uintptr_t)kt;
;     const int* pt = (const int*)a.in[I_PT + z] + s * NPAGES + wave * 8;
;     const float* cckv = (const float*)a.in[I_CCKV + z]; const float* ckr = (const float*)a.in[I_CKR + z];
;     float m_run = -1e30f, l_part = 0.f;
;     f32x4 oacc[16];
; #pragma unroll
;     for (int i = 0; i < 16; ++i) oacc[i] = (f32x4){0.f, 0.f, 0.f, 0.f};
;     f32x4 stA[18], stB[18];
;     ...
;     SA_ISSUE(stA, 0); SA_ISSUE(stB, 1);
.LBB0_1346:
	s_or_b64 exec, exec, s[6:7]
	s_waitcnt lgkmcnt(0)
	s_barrier
	s_load_dwordx2 s[4:5], s[18:19], 0x40
	s_lshl_b32 s6, s24, 6
	s_ashr_i32 s7, s6, 31
	s_lshl_b64 s[6:7], s[6:7], 2
	v_mov_b32_e32 v0, s33
	s_waitcnt lgkmcnt(0)
	s_add_u32 s38, s4, s6
	s_addc_u32 s39, s5, s7
	global_load_dword v2, v0, s[38:39]
	s_load_dwordx4 s[4:7], s[18:19], 0x20
	s_add_u32 s18, s38, s33
	s_addc_u32 s19, s39, 0
	v_and_b32_e32 v218, 63, v66
	v_and_b32_e32 v255, 7, v218
	v_lshlrev_b32_e32 v255, 2, v255
	global_load_dword v255, v255, s[18:19]
	v_lshlrev_b32_e32 v0, 4, v218
	v_and_b32_e32 v232, 48, v66
	s_waitcnt lgkmcnt(0)
	v_lshl_add_u64 v[220:221], s[4:5], 0, v[0:1]
	v_lshl_add_u64 v[222:223], s[6:7], 0, v[0:1]
	s_mov_b32 s1, 48
	v_mov_b32_e32 v216, 0
	v_mov_b32_e32 v233, 0xf149f2ca
	s_waitcnt vmcnt(0)
	v_readfirstlane_b32 s38, v2
	s_ashr_i32 s39, s38, 31
	s_lshl_b64 s[40:41], s[38:39], 17
	s_add_u32 s40, s4, s40
	s_addc_u32 s41, s5, s41
	v_lshl_add_u64 v[2:3], s[40:41], 0, v[0:1]
	v_add_co_u32_e32 v4, vcc, s34, v2
	s_lshl_b64 s[42:43], s[38:39], 14
	s_nop 0
	v_addc_co_u32_e32 v5, vcc, 0, v3, vcc
	global_load_dwordx4 v[68:71], v0, s[40:41] nt
	global_load_dwordx4 v[72:75], v0, s[40:41] offset:1024 nt
	global_load_dwordx4 v[76:79], v0, s[40:41] offset:2048 nt
	global_load_dwordx4 v[80:83], v0, s[40:41] offset:3072 nt
	s_add_u32 s40, s6, s42
	v_add_co_u32_e32 v6, vcc, s35, v2
	s_addc_u32 s41, s7, s43
	s_nop 0
	v_addc_co_u32_e32 v7, vcc, 0, v3, vcc
	s_lshl_b64 s[38:39], s[38:39], 7
	v_add_co_u32_e32 v2, vcc, s36, v2
	s_or_b32 s38, s38, 16
	s_nop 0
	v_addc_co_u32_e32 v3, vcc, 0, v3, vcc
	global_load_dwordx4 v[84:87], v[4:5], off offset:1024 nt
	global_load_dwordx4 v[88:91], v[4:5], off offset:2048 nt
	global_load_dwordx4 v[92:95], v[6:7], off offset:-4096 nt
	global_load_dwordx4 v[96:99], v[6:7], off nt
	global_load_dwordx4 v[100:103], v[6:7], off offset:1024 nt
	global_load_dwordx4 v[108:111], v[6:7], off offset:2048 nt
	global_load_dwordx4 v[120:123], v[4:5], off offset:3072 nt
	global_load_dwordx4 v[128:131], v[2:3], off nt
	global_load_dwordx4 v[132:135], v[2:3], off offset:1024 nt
	global_load_dwordx4 v[136:139], v[2:3], off offset:2048 nt
	global_load_dwordx4 v[140:143], v0, s[40:41] nt
	global_load_dwordx4 v[144:147], v0, s[40:41] offset:1024 nt
	global_load_dwordx4 v[160:163], v[6:7], off offset:3072 nt
	global_load_dwordx4 v[180:183], v[2:3], off offset:3072 nt
	s_lshl_b64 s[40:41], s[38:39], 10
	s_add_u32 s40, s4, s40
	s_addc_u32 s41, s5, s41
	v_lshl_add_u64 v[4:5], s[40:41], 0, v[0:1]
	v_add_co_u32_e32 v8, vcc, s34, v4
	s_lshl_b64 s[38:39], s[38:39], 7
	s_nop 0
	v_addc_co_u32_e32 v9, vcc, 0, v5, vcc
	v_add_co_u32_e32 v10, vcc, s35, v4
	s_add_u32 s38, s6, s38
	s_nop 0
	v_addc_co_u32_e32 v11, vcc, 0, v5, vcc
	v_add_co_u32_e32 v4, vcc, s36, v4
	global_load_dwordx4 v[104:107], v0, s[40:41] nt
	global_load_dwordx4 v[112:115], v0, s[40:41] offset:1024 nt
	global_load_dwordx4 v[116:119], v0, s[40:41] offset:2048 nt
	global_load_dwordx4 v[124:127], v0, s[40:41] offset:3072 nt
	v_addc_co_u32_e32 v5, vcc, 0, v5, vcc
	s_addc_u32 s39, s7, s39
	global_load_dwordx4 v[152:155], v[10:11], off offset:-4096 nt
	global_load_dwordx4 v[148:151], v[8:9], off offset:1024 nt
	global_load_dwordx4 v[156:159], v[8:9], off offset:2048 nt
	global_load_dwordx4 v[172:175], v[8:9], off offset:3072 nt
	global_load_dwordx4 v[164:167], v[10:11], off nt
	global_load_dwordx4 v[168:171], v[10:11], off offset:1024 nt
	global_load_dwordx4 v[176:179], v[10:11], off offset:2048 nt
	global_load_dwordx4 v[184:187], v[10:11], off offset:3072 nt
	global_load_dwordx4 v[188:191], v[4:5], off nt
	global_load_dwordx4 v[192:195], v[4:5], off offset:1024 nt
	global_load_dwordx4 v[196:199], v[4:5], off offset:2048 nt
	global_load_dwordx4 v[200:203], v[4:5], off offset:3072 nt
	global_load_dwordx4 v[204:207], v0, s[38:39] nt
	global_load_dwordx4 v[208:211], v0, s[38:39] offset:1024 nt
	v_lshlrev_b32_e32 v3, 3, v66
	v_bfe_u32 v8, v66, 2, 4
	v_bfe_u32 v2, v66, 3, 3
	v_and_b32_e32 v6, 56, v3
	v_mov_b32_e32 v7, s26
	v_mul_u32_u24_e32 v8, 0x250, v8
	v_and_b32_e32 v3, 24, v3
	v_mad_u32_u24 v4, v231, s31, 0
	v_lshlrev_b32_e32 v5, 3, v218
	v_add_u32_e32 v6, s26, v6
	v_mad_u32_u24 v7, v231, s31, v7
	v_add3_u32 v217, v3, s27, v8
	v_mul_u32_u24_e32 v8, 0x250, v2
	v_mov_b32_e32 v2, v1
	v_mov_b32_e32 v3, v1
	v_mov_b32_e32 v0, v1
	v_add_u32_e32 v236, s26, v5
	v_add_u32_e32 v237, v6, v8
	v_add_u32_e32 v235, v7, v232
	v_add_u32_e32 v234, v4, v232
	v_mov_b64_e32 v[6:7], v[2:3]
	v_mov_b64_e32 v[10:11], v[2:3]
	v_mov_b64_e32 v[14:15], v[2:3]
	v_mov_b64_e32 v[18:19], v[2:3]
	v_mov_b64_e32 v[22:23], v[2:3]
	v_mov_b64_e32 v[26:27], v[2:3]
	v_mov_b64_e32 v[30:31], v[2:3]
	v_mov_b64_e32 v[34:35], v[2:3]
	v_mov_b64_e32 v[38:39], v[2:3]
	v_mov_b64_e32 v[42:43], v[2:3]
	v_mov_b64_e32 v[46:47], v[2:3]
	v_mov_b64_e32 v[50:51], v[2:3]
	v_mov_b64_e32 v[54:55], v[2:3]
	v_mov_b64_e32 v[58:59], v[2:3]
	v_mov_b64_e32 v[62:63], v[2:3]
	v_mov_b64_e32 v[66:67], v[2:3]
	s_mov_b32 s38, 3
	v_mov_b64_e32 v[4:5], v[0:1]
	v_mov_b64_e32 v[8:9], v[0:1]
	v_mov_b64_e32 v[12:13], v[0:1]
	v_mov_b64_e32 v[16:17], v[0:1]
	v_mov_b64_e32 v[20:21], v[0:1]
	v_mov_b64_e32 v[24:25], v[0:1]
	v_mov_b64_e32 v[28:29], v[0:1]
	v_mov_b64_e32 v[32:33], v[0:1]
	v_mov_b64_e32 v[36:37], v[0:1]
	v_mov_b64_e32 v[40:41], v[0:1]
	v_mov_b64_e32 v[44:45], v[0:1]
	v_mov_b64_e32 v[48:49], v[0:1]
	v_mov_b64_e32 v[52:53], v[0:1]
	v_mov_b64_e32 v[56:57], v[0:1]
	v_mov_b64_e32 v[60:61], v[0:1]
	v_mov_b64_e32 v[64:65], v[0:1]
; #define VM_WAIT() asm volatile("s_waitcnt vmcnt(0)" ::: "memory")
; __device__ __forceinline__ void sample_attn_seq(const Args& a, LAS unsigned char* lds, int s, int wv) {
;     ...
;     for (int tt = 0; tt < 64; tt += 2) {
;         if (tt + 1 < 64) asm volatile("s_waitcnt vmcnt(18)" ::: "memory"); else VM_WAIT();
;         asm volatile("" : "+v"(stA[0]), "+v"(stA[1]), "+v"(stA[2]), "+v"(stA[3]), "+v"(stA[4]), "+v"(stA[5]), "+v"(stA[6]), "+v"(stA[7]), "+v"(stA[8]));
;         asm volatile("" : "+v"(stA[9]), "+v"(stA[10]), "+v"(stA[11]), "+v"(stA[12]), "+v"(stA[13]), "+v"(stA[14]), "+v"(stA[15]), "+v"(stA[16]), "+v"(stA[17]));
;         SA_TOLDS(stA);
;         if (tt + 2 < 64) SA_ISSUE(stA, tt + 2);
;         SA_COMPUTE(false);
.LBB0_1347:
	s_waitcnt vmcnt(18)
	v_add_u32_e32 v238, 0x2000, v236
	v_cvt_pk_bf16_f32 v2, v68, v69
	v_cvt_pk_bf16_f32 v3, v70, v71
	v_cvt_pk_bf16_f32 v212, v72, v73
	v_cvt_pk_bf16_f32 v213, v74, v75
	ds_write2_b64 v238, v[2:3], v[212:213] offset0:160 offset1:234
	v_cvt_pk_bf16_f32 v2, v76, v77
	v_cvt_pk_bf16_f32 v3, v78, v79
	v_cvt_pk_bf16_f32 v212, v80, v81
	v_cvt_pk_bf16_f32 v213, v82, v83
	v_add_u32_e32 v239, 0x2800, v236
	ds_write2_b64 v239, v[2:3], v[212:213] offset0:52 offset1:126
	v_cvt_pk_bf16_f32 v2, v92, v93
	v_cvt_pk_bf16_f32 v3, v94, v95
	v_cvt_pk_bf16_f32 v212, v84, v85
	v_cvt_pk_bf16_f32 v213, v86, v87
	v_add_u32_e32 v240, 0x2c00, v236
	ds_write2_b64 v240, v[2:3], v[212:213] offset0:72 offset1:146
	v_cvt_pk_bf16_f32 v2, v88, v89
	v_cvt_pk_bf16_f32 v3, v90, v91
	v_cvt_pk_bf16_f32 v212, v120, v121
	v_cvt_pk_bf16_f32 v213, v122, v123
	v_add_u32_e32 v241, 0x3000, v236
	ds_write2_b64 v241, v[2:3], v[212:213] offset0:92 offset1:166
	v_cvt_pk_bf16_f32 v2, v96, v97
	v_cvt_pk_bf16_f32 v3, v98, v99
	v_cvt_pk_bf16_f32 v212, v100, v101
	v_cvt_pk_bf16_f32 v213, v102, v103
	v_add_u32_e32 v242, 0x3400, v236
	ds_write2_b64 v242, v[2:3], v[212:213] offset0:112 offset1:186
	v_cvt_pk_bf16_f32 v2, v108, v109
	v_cvt_pk_bf16_f32 v3, v110, v111
	v_cvt_pk_bf16_f32 v212, v160, v161
	v_cvt_pk_bf16_f32 v213, v162, v163
	v_add_u32_e32 v243, 0x3800, v236
	s_add_i32 s39, s38, -3
	ds_write2_b64 v243, v[2:3], v[212:213] offset0:132 offset1:206
	v_cvt_pk_bf16_f32 v2, v128, v129
	v_cvt_pk_bf16_f32 v3, v130, v131
	v_cvt_pk_bf16_f32 v212, v132, v133
	v_cvt_pk_bf16_f32 v213, v134, v135
	v_add_u32_e32 v244, 0x4000, v236
	ds_write2_b64 v244, v[2:3], v[212:213] offset0:24 offset1:98
	v_cvt_pk_bf16_f32 v2, v136, v137
	v_cvt_pk_bf16_f32 v3, v138, v139
	v_cvt_pk_bf16_f32 v212, v180, v181
	v_cvt_pk_bf16_f32 v213, v182, v183
	s_cmp_gt_u32 s39, 61
	ds_write2_b64 v244, v[2:3], v[212:213] offset0:172 offset1:246
	v_cvt_pk_bf16_f32 v2, v140, v141
	v_cvt_pk_bf16_f32 v3, v142, v143
	s_cselect_b64 s[4:5], -1, 0
	ds_write_b64 v237, v[2:3] offset:9984
	v_cvt_pk_bf16_f32 v2, v144, v145
	v_cvt_pk_bf16_f32 v3, v146, v147
	s_and_b64 vcc, exec, s[4:5]
	ds_write_b64 v237, v[2:3] offset:14720
	s_cbranch_vccnz .LBB0_1349
	s_add_i32 s6, s38, -1
	s_lshr_b32 s6, s6, 3
	s_nop 0
	v_readlane_b32 s99, v255, s6
	s_add_i32 s6, s1, -16
	s_and_b32 s6, s6, 0x60
	s_nop 0
	v_mov_b32_e32 v2, s99
	v_ashrrev_i32_e32 v3, 31, v2
	v_lshlrev_b64 v[2:3], 7, v[2:3]
	v_or_b32_e32 v2, s6, v2
	v_lshlrev_b64 v[68:69], 10, v[2:3]
	v_lshl_add_u64 v[120:121], v[220:221], 0, v[68:69]
	v_add_co_u32_e32 v122, vcc, s34, v120
	v_lshlrev_b64 v[2:3], 7, v[2:3]
	s_nop 0
	v_addc_co_u32_e32 v123, vcc, 0, v121, vcc
	v_add_co_u32_e32 v128, vcc, s35, v120
	v_lshl_add_u64 v[2:3], v[222:223], 0, v[2:3]
	s_nop 0
	v_addc_co_u32_e32 v129, vcc, 0, v121, vcc
	v_add_co_u32_e32 v140, vcc, 0x3000, v120
	global_load_dwordx4 v[68:71], v[120:121], off nt
	global_load_dwordx4 v[72:75], v[120:121], off offset:1024 nt
	global_load_dwordx4 v[76:79], v[120:121], off offset:2048 nt
	global_load_dwordx4 v[80:83], v[120:121], off offset:3072 nt
	v_addc_co_u32_e32 v141, vcc, 0, v121, vcc
	global_load_dwordx4 v[84:87], v[122:123], off offset:1024 nt
	global_load_dwordx4 v[88:91], v[122:123], off offset:2048 nt
	global_load_dwordx4 v[92:95], v[128:129], off offset:-4096 nt
	global_load_dwordx4 v[96:99], v[128:129], off nt
	global_load_dwordx4 v[100:103], v[128:129], off offset:1024 nt
	global_load_dwordx4 v[108:111], v[128:129], off offset:2048 nt
	global_load_dwordx4 v[160:163], v[128:129], off offset:3072 nt
	s_nop 0
	global_load_dwordx4 v[120:123], v[122:123], off offset:3072 nt
	s_nop 0
	global_load_dwordx4 v[128:131], v[140:141], off nt
	global_load_dwordx4 v[132:135], v[140:141], off offset:1024 nt
	global_load_dwordx4 v[136:139], v[140:141], off offset:2048 nt
	global_load_dwordx4 v[180:183], v[140:141], off offset:3072 nt
	s_nop 0
	global_load_dwordx4 v[140:143], v[2:3], off nt
	global_load_dwordx4 v[144:147], v[2:3], off offset:1024 nt

; #define VM_WAIT() asm volatile("s_waitcnt vmcnt(0)" ::: "memory")
; __device__ __forceinline__ void sample_attn_seq(const Args& a, LAS unsigned char* lds, int s, int wv) {
;     ...
;         if (tt + 2 < 64) asm volatile("s_waitcnt vmcnt(18)" ::: "memory"); else VM_WAIT();
;         asm volatile("" : "+v"(stB[0]), "+v"(stB[1]), "+v"(stB[2]), "+v"(stB[3]), "+v"(stB[4]), "+v"(stB[5]), "+v"(stB[6]), "+v"(stB[7]), "+v"(stB[8]));
;         asm volatile("" : "+v"(stB[9]), "+v"(stB[10]), "+v"(stB[11]), "+v"(stB[12]), "+v"(stB[13]), "+v"(stB[14]), "+v"(stB[15]), "+v"(stB[16]), "+v"(stB[17]));
;         SA_TOLDS(stB);
;         if (tt + 3 < 64) SA_ISSUE(stB, tt + 3);
.LBB0_1354:
	s_cmp_gt_u32 s39, 60
	v_cvt_pk_bf16_f32 v6, v104, v105
	v_cvt_pk_bf16_f32 v7, v106, v107
	v_cvt_pk_bf16_f32 v246, v112, v113
	v_cvt_pk_bf16_f32 v247, v114, v115
	ds_write2_b64 v238, v[6:7], v[246:247] offset0:160 offset1:234
	v_cvt_pk_bf16_f32 v6, v116, v117
	v_cvt_pk_bf16_f32 v7, v118, v119
	v_cvt_pk_bf16_f32 v246, v124, v125
	v_cvt_pk_bf16_f32 v247, v126, v127
	ds_write2_b64 v239, v[6:7], v[246:247] offset0:52 offset1:126
	v_cvt_pk_bf16_f32 v6, v152, v153
	v_cvt_pk_bf16_f32 v7, v154, v155
	v_cvt_pk_bf16_f32 v246, v148, v149
	v_cvt_pk_bf16_f32 v247, v150, v151
	ds_write2_b64 v240, v[6:7], v[246:247] offset0:72 offset1:146
	v_cvt_pk_bf16_f32 v6, v156, v157
	v_cvt_pk_bf16_f32 v7, v158, v159
	v_cvt_pk_bf16_f32 v246, v172, v173
	v_cvt_pk_bf16_f32 v247, v174, v175
	ds_write2_b64 v241, v[6:7], v[246:247] offset0:92 offset1:166
	v_cvt_pk_bf16_f32 v6, v164, v165
	v_cvt_pk_bf16_f32 v7, v166, v167
	v_cvt_pk_bf16_f32 v246, v168, v169
	v_cvt_pk_bf16_f32 v247, v170, v171
	ds_write2_b64 v242, v[6:7], v[246:247] offset0:112 offset1:186
	v_cvt_pk_bf16_f32 v6, v176, v177
	v_cvt_pk_bf16_f32 v7, v178, v179
	v_cvt_pk_bf16_f32 v246, v184, v185
	v_cvt_pk_bf16_f32 v247, v186, v187
	ds_write2_b64 v243, v[6:7], v[246:247] offset0:132 offset1:206
	v_cvt_pk_bf16_f32 v6, v188, v189
	v_cvt_pk_bf16_f32 v7, v190, v191
	v_cvt_pk_bf16_f32 v246, v192, v193
	v_cvt_pk_bf16_f32 v247, v194, v195
	ds_write2_b64 v244, v[6:7], v[246:247] offset0:24 offset1:98
	v_cvt_pk_bf16_f32 v6, v196, v197
	v_cvt_pk_bf16_f32 v7, v198, v199
	v_cvt_pk_bf16_f32 v246, v200, v201
	v_cvt_pk_bf16_f32 v247, v202, v203
	ds_write2_b64 v244, v[6:7], v[246:247] offset0:172 offset1:246
	v_cvt_pk_bf16_f32 v6, v204, v205
	v_cvt_pk_bf16_f32 v7, v206, v207
	ds_write_b64 v237, v[6:7] offset:9984
	v_cvt_pk_bf16_f32 v6, v208, v209
	v_cvt_pk_bf16_f32 v7, v210, v211
	ds_write_b64 v237, v[6:7] offset:14720
	s_cbranch_scc1 .LBB0_1356
	s_lshr_b32 s4, s38, 3
	s_nop 0
	v_readlane_b32 s99, v255, s4
	s_and_b32 s4, s1, 0x70
	s_nop 1
	v_mov_b32_e32 v6, s99
	v_ashrrev_i32_e32 v7, 31, v6
	v_lshlrev_b64 v[6:7], 7, v[6:7]
	v_or_b32_e32 v6, s4, v6
	v_lshlrev_b64 v[104:105], 10, v[6:7]
	v_lshl_add_u64 v[172:173], v[220:221], 0, v[104:105]
	v_add_co_u32_e32 v174, vcc, s34, v172
	v_lshlrev_b64 v[6:7], 7, v[6:7]
	s_nop 0
	v_addc_co_u32_e32 v175, vcc, 0, v173, vcc
	v_add_co_u32_e32 v184, vcc, s35, v172
	v_lshl_add_u64 v[6:7], v[222:223], 0, v[6:7]
	s_nop 0
	v_addc_co_u32_e32 v185, vcc, 0, v173, vcc
	v_add_co_u32_e32 v200, vcc, 0x3000, v172
	global_load_dwordx4 v[104:107], v[172:173], off nt
	global_load_dwordx4 v[112:115], v[172:173], off offset:1024 nt
	global_load_dwordx4 v[116:119], v[172:173], off offset:2048 nt
	global_load_dwordx4 v[124:127], v[172:173], off offset:3072 nt
	v_addc_co_u32_e32 v201, vcc, 0, v173, vcc
	global_load_dwordx4 v[148:151], v[174:175], off offset:1024 nt
	global_load_dwordx4 v[156:159], v[174:175], off offset:2048 nt
	global_load_dwordx4 v[152:155], v[184:185], off offset:-4096 nt
	global_load_dwordx4 v[164:167], v[184:185], off nt
	global_load_dwordx4 v[168:171], v[184:185], off offset:1024 nt
	global_load_dwordx4 v[176:179], v[184:185], off offset:2048 nt
	s_nop 0
	global_load_dwordx4 v[184:187], v[184:185], off offset:3072 nt
	s_nop 0
	global_load_dwordx4 v[172:175], v[174:175], off offset:3072 nt
	s_nop 0
	global_load_dwordx4 v[188:191], v[200:201], off nt
	global_load_dwordx4 v[192:195], v[200:201], off offset:1024 nt
	global_load_dwordx4 v[196:199], v[200:201], off offset:2048 nt
	s_nop 0
	global_load_dwordx4 v[200:203], v[200:201], off offset:3072 nt
	s_nop 0
	global_load_dwordx4 v[204:207], v[6:7], off nt
	global_load_dwordx4 v[208:211], v[6:7], off offset:1024 nt

; #define SBAR() __builtin_amdgcn_sched_barrier(0)
; #define DMA_K(t, slot) do { if constexpr ((VAR & 16) != 0) break; __builtin_amdgcn_global_load_lds((const unsigned*)(ksrc + (size_t)TT(t) * 64 * KVW), (LAS unsigned*)(kdst + (slot) * KSLOT), 16, 0, 0); \
;                             __builtin_amdgcn_global_load_lds((const unsigned*)(rsrc + (size_t)TT(t) * 64 * ROPE), (LAS unsigned*)(rdst + (slot) * KSLOT), 16, 0, 0); } while (0)
; #define DMA_V(t, slot) do { if constexpr ((VAR & 16) == 0) __builtin_amdgcn_global_load_lds((const unsigned*)(vsrc + (size_t)TT(t) * 64 * KVW), (LAS unsigned*)(vdst + (slot) * VSLOT), 16, 0, 0); } while (0)
; #define KLOAD(slot) do { const LAS unsigned char* kb_ = kb0 + (slot) * KSLOT; _Pragma("unroll") for (int d0 = 0; d0 < 6; ++d0) { kf[2 * d0] = *(const LAS bf16x8*)(kb_ + d0 * 512); kf[2 * d0 + 1] = *(const LAS bf16x8*)(kb_ + d0 * 512 + 6144); } } while (0)
; #define VREAD(slot) do { const int vb_ = vb0 + (slot) * VSLOT; \
;         TRRD(vl[0], 0); TRRD(vh[0], 512); TRRD(vl[1], 1024); TRRD(vh[1], 1536); TRRD(vl[2], 2048); TRRD(vh[2], 2560); TRRD(vl[3], 3072); TRRD(vh[3], 3584); \
;         TRRD(vl[4], 4096); TRRD(vh[4], 4608); TRRD(vl[5], 5120); TRRD(vh[5], 5632); TRRD(vl[6], 6144); TRRD(vh[6], 6656); TRRD(vl[7], 7168); TRRD(vh[7], 7680); } while (0)
; template <int VAR> __device__ __forceinline__ void block(const bf16* Q, const bf16* KVB, const bf16* KR, const float* cosT, bf16* OB, LAS unsigned char* lds, int b, int h, int qb, int t0, int wv, ...
;     ...
;         { if (t + 3 < NT) DMA_K(t + 3, (sk + 3) & 3); if (t + 2 < NT) DMA_V(t + 2, (sk + 2) & 3); }
;         SBAR();
;         KLOAD(sk); VREAD(sv);
;         SBAR();
;         QK(px0, px1);
.Lat_mreads:
	s_setprio 1
	s_mul_i32 s98, s82, 0x3000
	v_add_u32_e32 v52, s98, v149
	v_lshl_add_u32 v255, s68, 13, v172
	ds_read_b128 v[48:51], v52
	ds_read_b128 v[174:177], v52 offset:512
	ds_read_b128 v[178:181], v52 offset:6144
	ds_read_b128 v[182:185], v52 offset:6656
	ds_read_b128 v[186:189], v52 offset:1024
	ds_read_b128 v[194:197], v52 offset:7168
	ds_read_b128 v[190:193], v52 offset:1536
	ds_read_b128 v[198:201], v52 offset:7680
	ds_read_b128 v[202:205], v52 offset:2048
	ds_read_b128 v[210:213], v52 offset:8192
	ds_read_b128 v[206:209], v52 offset:2560
	ds_read_b128 v[214:217], v52 offset:8704
	ds_read_b64_tr_b16 v[220:221], v255 offset:0x0
	ds_read_b64_tr_b16 v[222:223], v255 offset:0x200
	ds_read_b64_tr_b16 v[226:227], v255 offset:0x400
	s_waitcnt lgkmcnt(14)
	v_mfma_f32_32x32x16_bf16 v[64:79], v[48:51], v[112:115], v[32:47]
	v_mov_b64_e32 v[62:63], v[46:47]
	v_mov_b64_e32 v[60:61], v[44:45]
	v_mov_b64_e32 v[58:59], v[42:43]
	v_mov_b64_e32 v[56:57], v[40:41]
	v_mov_b64_e32 v[54:55], v[38:39]
	v_mov_b64_e32 v[52:53], v[36:37]
	v_mov_b64_e32 v[50:51], v[34:35]
	v_mov_b64_e32 v[48:49], v[32:33]
	ds_read_b64_tr_b16 v[228:229], v255 offset:0x600
	s_waitcnt lgkmcnt(14)
	v_mfma_f32_32x32x16_bf16 v[64:79], v[174:177], v[104:107], v[64:79]
	ds_read_b64_tr_b16 v[230:231], v255 offset:0x800
	s_waitcnt lgkmcnt(14)
	v_mfma_f32_32x32x16_bf16 v[48:63], v[178:181], v[112:115], v[48:63]
	ds_read_b64_tr_b16 v[232:233], v255 offset:0xa00
	s_waitcnt lgkmcnt(14)
	v_mfma_f32_32x32x16_bf16 v[48:63], v[182:185], v[104:107], v[48:63]
	s_cmp_lt_u32 s85, s66
	s_cbranch_scc0 .Lat_nodmak
	s_add_i32 s98, s82, -1
	s_and_b32 s98, s98, 3
	s_mulk_i32 s98, 0x3000
	s_add_i32 m0, s1, s98
	s_add_i32 s98, s0, s98
	global_load_lds_dwordx4 v[158:159], off
	s_add_i32 m0, s98, 0x800
	s_nop 0
	global_load_lds_dwordx4 v[156:157], off

; #define SBAR() __builtin_amdgcn_sched_barrier(0)
; #define KLOAD(slot) do { const LAS unsigned char* kb_ = kb0 + (slot) * KSLOT; _Pragma("unroll") for (int d0 = 0; d0 < 6; ++d0) { kf[2 * d0] = *(const LAS bf16x8*)(kb_ + d0 * 512); kf[2 * d0 + 1] = *(const LAS bf16x8*)(kb_ + d0 * 512 + 6144); } } while (0)
; #define VREAD(slot) do { const int vb_ = vb0 + (slot) * VSLOT; \
;         TRRD(vl[0], 0); TRRD(vh[0], 512); TRRD(vl[1], 1024); TRRD(vh[1], 1536); TRRD(vl[2], 2048); TRRD(vh[2], 2560); TRRD(vl[3], 3072); TRRD(vh[3], 3584); \
;         TRRD(vl[4], 4096); TRRD(vh[4], 4608); TRRD(vl[5], 5120); TRRD(vh[5], 5632); TRRD(vl[6], 6144); TRRD(vh[6], 6656); TRRD(vl[7], 7168); TRRD(vh[7], 7680); } while (0)
; template <int VAR> __device__ __forceinline__ void block(const bf16* Q, const bf16* KVB, const bf16* KR, const float* cosT, bf16* OB, LAS unsigned char* lds, int b, int h, int qb, int t0, int wv, ...
;     ...
;         KLOAD(sk); VREAD(sv);
;         SBAR();
;         QK(px0, px1);
;         SBAR(); asm volatile("s_waitcnt lgkmcnt(0)" ::: "memory"); SBAR();
;         PVALL();
.Lat_nodmav:
	ds_read_b64_tr_b16 v[238:239], v255 offset:0x1000
	s_waitcnt lgkmcnt(14)
	v_mfma_f32_32x32x16_bf16 v[64:79], v[190:193], v[108:111], v[64:79]
	ds_read_b64_tr_b16 v[240:241], v255 offset:0x1200
	s_waitcnt lgkmcnt(14)
	v_mfma_f32_32x32x16_bf16 v[48:63], v[198:201], v[108:111], v[48:63]
	ds_read_b64_tr_b16 v[242:243], v255 offset:0x1400
	s_waitcnt lgkmcnt(14)
	v_mfma_f32_32x32x16_bf16 v[64:79], v[202:205], v[120:123], v[64:79]
	ds_read_b64_tr_b16 v[244:245], v255 offset:0x1600
	s_waitcnt lgkmcnt(14)
	v_mfma_f32_32x32x16_bf16 v[48:63], v[210:213], v[120:123], v[48:63]
	ds_read_b64_tr_b16 v[246:247], v255 offset:0x1800
	s_waitcnt lgkmcnt(14)
	v_mfma_f32_32x32x16_bf16 v[64:79], v[206:209], v[124:127], v[64:79]
	ds_read_b64_tr_b16 v[248:249], v255 offset:0x1a00
	s_waitcnt lgkmcnt(14)
	v_mfma_f32_32x32x16_bf16 v[48:63], v[214:217], v[124:127], v[48:63]
	ds_read_b64_tr_b16 v[250:251], v255 offset:0x1c00
	ds_read_b64_tr_b16 v[252:253], v255 offset:0x1e00
	s_waitcnt lgkmcnt(14)
	v_mfma_f32_32x32x16_bf16 v[16:31], v[140:143], v[220:223], v[16:31]
	s_mov_b64 s[6:7], -1
	s_and_b64 vcc, exec, s[4:5]
	s_waitcnt lgkmcnt(12)
	v_mfma_f32_32x32x16_bf16 v[16:31], v[136:139], v[226:229], v[16:31]
	s_waitcnt lgkmcnt(10)
	v_mfma_f32_32x32x16_bf16 v[16:31], v[132:135], v[230:233], v[16:31]
	s_waitcnt lgkmcnt(8)
	v_mfma_f32_32x32x16_bf16 v[16:31], v[128:131], v[234:237], v[16:31]
	s_waitcnt lgkmcnt(6)
	v_mfma_f32_32x32x16_bf16 v[0:15], v[140:143], v[238:241], v[0:15]
	s_waitcnt lgkmcnt(4)
	v_mfma_f32_32x32x16_bf16 v[0:15], v[136:139], v[242:245], v[0:15]
	s_waitcnt lgkmcnt(2)
	v_mfma_f32_32x32x16_bf16 v[0:15], v[132:135], v[246:249], v[0:15]
	s_waitcnt lgkmcnt(0)
	v_mfma_f32_32x32x16_bf16 v[0:15], v[128:131], v[250:253], v[0:15]
	s_setprio 0
	s_cbranch_vccnz .LBB0_1427
	s_andn2_b64 vcc, exec, s[6:7]
	s_cbranch_vccz .LBB0_1428

; #define LAS __attribute__((address_space(3)))
; __global__ void __launch_bounds__(NWAVES * 64, 2) hybrid_fwd(Args args) {
;     extern __shared__ __attribute__((aligned(16))) unsigned char lds_raw[];
;     LAS unsigned char* lds = (LAS unsigned char*)lds_raw;
;     const int wv0 = __builtin_amdgcn_readfirstlane(threadIdx.x >> 6);
	.amdhsa_kernel _Z10hybrid_fwd4Args
		.amdhsa_group_segment_fixed_size 0
		.amdhsa_private_segment_fixed_size 0
		.amdhsa_kernarg_size 616
		.amdhsa_user_sgpr_count 2
		.amdhsa_user_sgpr_dispatch_ptr 0
		.amdhsa_user_sgpr_queue_ptr 0
		.amdhsa_user_sgpr_kernarg_segment_ptr 1
		.amdhsa_user_sgpr_dispatch_id 0
		.amdhsa_user_sgpr_kernarg_preload_length 0
		.amdhsa_user_sgpr_kernarg_preload_offset 0
		.amdhsa_user_sgpr_private_segment_size 0
		.amdhsa_uses_dynamic_stack 0
		.amdhsa_enable_private_segment 0
		.amdhsa_system_sgpr_workgroup_id_x 1
		.amdhsa_system_sgpr_workgroup_id_y 0
		.amdhsa_system_sgpr_workgroup_id_z 0
		.amdhsa_system_sgpr_workgroup_info 0
		.amdhsa_system_vgpr_workitem_id 0
		.amdhsa_next_free_vgpr 256
		.amdhsa_next_free_sgpr 100
		.amdhsa_accum_offset 256
		.amdhsa_reserve_vcc 1
		.amdhsa_float_round_mode_32 0
		.amdhsa_float_round_mode_16_64 0
		.amdhsa_float_denorm_mode_32 3
		.amdhsa_float_denorm_mode_16_64 3
		.amdhsa_dx10_clamp 1
		.amdhsa_ieee_mode 1
		.amdhsa_fp16_overflow 0
		.amdhsa_tg_split 0
		.amdhsa_exception_fp_ieee_invalid_op 0
		.amdhsa_exception_fp_denorm_src 0
		.amdhsa_exception_fp_ieee_div_zero 0
		.amdhsa_exception_fp_ieee_overflow 0
		.amdhsa_exception_fp_ieee_underflow 0
		.amdhsa_exception_fp_ieee_inexact 0
		.amdhsa_exception_int_div_zero 0
	.end_amdhsa_kernel

; #define LAS __attribute__((address_space(3)))
; __global__ void __launch_bounds__(NWAVES * 64, 2) hybrid_fwd(Args args) {
;     extern __shared__ __attribute__((aligned(16))) unsigned char lds_raw[];
;     LAS unsigned char* lds = (LAS unsigned char*)lds_raw;
;     const int wv0 = __builtin_amdgcn_readfirstlane(threadIdx.x >> 6);
amdhsa.kernels:
  - .agpr_count:     0
    .args:
      - .offset:         0
        .size:           360
        .value_kind:     by_value
      - .offset:         360
        .size:           4
        .value_kind:     hidden_block_count_x
      - .offset:         364
        .size:           4
        .value_kind:     hidden_block_count_y
      - .offset:         368
        .size:           4
        .value_kind:     hidden_block_count_z
      - .offset:         372
        .size:           2
        .value_kind:     hidden_group_size_x
      - .offset:         374
        .size:           2
        .value_kind:     hidden_group_size_y
      - .offset:         376
        .size:           2
        .value_kind:     hidden_group_size_z
      - .offset:         378
        .size:           2
        .value_kind:     hidden_remainder_x
      - .offset:         380
        .size:           2
        .value_kind:     hidden_remainder_y
      - .offset:         382
        .size:           2
        .value_kind:     hidden_remainder_z
      - .offset:         400
        .size:           8
        .value_kind:     hidden_global_offset_x
      - .offset:         408
        .size:           8
        .value_kind:     hidden_global_offset_y
      - .offset:         416
        .size:           8
        .value_kind:     hidden_global_offset_z
      - .offset:         424
        .size:           2
        .value_kind:     hidden_grid_dims
      - .offset:         480
        .size:           4
        .value_kind:     hidden_dynamic_lds_size
    .group_segment_fixed_size: 0
    .kernarg_segment_align: 8
    .kernarg_segment_size: 616
    .language:       OpenCL C
    .language_version:
      - 2
      - 0
    .max_flat_workgroup_size: 512
    .name:           _Z10hybrid_fwd4Args
    .private_segment_fixed_size: 0
    .sgpr_count:     106
    .sgpr_spill_count: 64
    .symbol:         _Z10hybrid_fwd4Args.kd
    .uniform_work_group_size: 1
    .uses_dynamic_stack: false
    .vgpr_count:     256
    .vgpr_spill_count: 0
    .wavefront_size: 64
